# GU unit-order arithmetic in 32-bit scalar ops (no float-reciprocal division, no vector compares)
# baseline (speedup 1.0000x reference)
.LBB0_1107:
	s_add_i32 s54, s54, 1
	s_mul_i32 s6, s54, s26
	s_add_i32 s6, s6, s2
	s_cmp_lt_u32 s6, 0x5c2
	s_cselect_b64 s[12:13], -1, 0
	s_cbranch_scc0 .LBB0_1113
	s_and_b32 s9, s6, 7
	s_lshr_b32 s8, s6, 3
	s_mul_i32 s10, s9, 0xb8
	s_min_u32 s9, s9, 2
	s_add_i32 s10, s10, s9
	s_add_i32 s6, s10, s8
	s_mul_hi_u32 s7, s6, 0x2e8ba2e9
	s_lshr_b32 s7, s7, 4
	s_lshl_b32 s8, s7, 2
	s_sub_i32 s9, 0x43, s8
	s_min_i32 s9, s9, 4
	s_mulk_i32 s7, 0x58
	s_sub_i32 s6, s6, s7
	s_cmp_eq_u32 s9, 4
	s_movk_i32 s7, 0x5556
	s_cselect_b32 s7, 0x4000, s7
	s_mul_i32 s68, s6, s7
	s_lshr_b32 s68, s68, 16
	s_mul_i32 s7, s68, s9
	s_sub_i32 s6, s6, s7
	s_add_i32 s70, s8, s6

.LBB0_2152:
	s_add_i32 s3, s3, 1
	s_mul_i32 s6, s3, s26
	s_add_i32 s6, s6, s2
	s_cmp_lt_u32 s6, 0x5c2
	s_cselect_b64 s[8:9], -1, 0
	s_cbranch_scc0 .LBB0_2158
	s_and_b32 s10, s6, 7
	s_lshr_b32 s1, s6, 3
	s_mul_i32 s15, s10, 0xb8
	s_min_u32 s10, s10, 2
	s_add_i32 s15, s15, s10
	s_add_i32 s6, s15, s1
	s_mul_hi_u32 s7, s6, 0x2e8ba2e9
	s_lshr_b32 s7, s7, 4
	s_lshl_b32 s1, s7, 2
	s_sub_i32 s10, 0x43, s1
	s_min_i32 s10, s10, 4
	s_mulk_i32 s7, 0x58
	s_sub_i32 s6, s6, s7
	s_cmp_eq_u32 s10, 4
	s_movk_i32 s7, 0x5556
	s_cselect_b32 s7, 0x4000, s7
	s_mul_i32 s54, s6, s7
	s_lshr_b32 s54, s54, 16
	s_mul_i32 s7, s54, s10
	s_sub_i32 s6, s6, s7
	s_add_i32 s56, s1, s6
